# diff-attention lambda (exp of two 64-wide dot products) computed once per attention phase instead of in every unit epilogue; SS prefetch also in the input-projection GEMM
# baseline (speedup 1.0000x reference)
;     __device__ __forceinline__ void operator()(const f32x4 (&acc)[2][2][4][2], const Unit& u, int wr, int wc, int fr_in, int fq_in) const {
;     ...
;         float ssv[2][4];
; #pragma unroll
;         for (int ai = 0; ai < 2; ++ai)
; #pragma unroll
;             for (int m = 0; m < 4; ++m) ssv[ai][m] = SS[row0 + ai * HALF + m * 16];
; template <class Epi, class Sched, bool ALIGN_EPI = false, bool SP2 = false>
; __device__ __forceinline__ void gemm_phase(PG8_LAS unsigned char* lds, const Gemm g, const Sched& S, const Epi& E) {
;     ...
;     f32x4 acc[2][2][4][2];
; #pragma unroll
;     for (int a = 0; a < 2; ++a)
; #pragma unroll
;         for (int b = 0; b < 2; ++b)
; #pragma unroll
;             for (int m = 0; m < 4; ++m)
; #pragma unroll
;                 for (int n = 0; n < 2; ++n) acc[a][b][m][n] = (f32x4){0.f, 0.f, 0.f, 0.f};
;     bf16x8 At[4][2], B0[2][2], B1[2][2];
;     const char* cA = (const char*)g.A + (size_t)cur.pm * tstep; const char* cB = (const char*)g.Bt + (size_t)cur.pn * tstep;
.LBB0_546:
	s_ashr_i32 s23, s22, 31
	s_lshl_b64 s[24:25], s[22:23], 19
	s_add_u32 s24, s58, s24
	s_addc_u32 s25, s59, s25
	s_and_b64 s[26:27], s[0:1], exec
	s_cselect_b32 s5, s25, s39
	s_cselect_b32 s23, s24, s38
	s_ashr_i32 s15, s14, 31
	s_lshl_b64 s[26:27], s[14:15], 19
	s_add_u32 s26, s30, s26
	s_addc_u32 s27, s40, s27
	s_and_b64 s[60:61], s[0:1], exec
	s_cselect_b32 s15, s27, s37
	s_cselect_b32 s73, s26, s36
	s_add_u32 s74, s36, 0x100
	s_addc_u32 s75, s37, 0
	s_add_u32 s60, s38, 0x40080
	v_mov_b32_e32 v2, 0
	s_addc_u32 s61, s39, 0
	s_mov_b32 s76, -2
	v_mov_b32_e32 v3, v2
	v_mov_b32_e32 v4, v2
	v_mov_b32_e32 v5, v2
	v_mov_b32_e32 v6, v2
	v_mov_b32_e32 v7, v2
	v_mov_b32_e32 v8, v2
	v_mov_b32_e32 v9, v2
	v_mov_b32_e32 v18, v2
	v_mov_b32_e32 v19, v2
	v_mov_b32_e32 v20, v2
	v_mov_b32_e32 v21, v2
	v_mov_b32_e32 v22, v2
	v_mov_b32_e32 v23, v2
	v_mov_b32_e32 v24, v2
	v_mov_b32_e32 v25, v2
	v_mov_b32_e32 v34, v2
	v_mov_b32_e32 v35, v2
	v_mov_b32_e32 v36, v2
	v_mov_b32_e32 v37, v2
	v_mov_b32_e32 v38, v2
	v_mov_b32_e32 v39, v2
	v_mov_b32_e32 v40, v2
	v_mov_b32_e32 v41, v2
	v_mov_b32_e32 v50, v2
	v_mov_b32_e32 v51, v2
	v_mov_b32_e32 v52, v2
	v_mov_b32_e32 v53, v2
	v_mov_b32_e32 v54, v2
	v_mov_b32_e32 v55, v2
	v_mov_b32_e32 v56, v2
	v_mov_b32_e32 v57, v2
	v_mov_b32_e32 v10, v2
	v_mov_b32_e32 v11, v2
	v_mov_b32_e32 v12, v2
	v_mov_b32_e32 v13, v2
	v_mov_b32_e32 v14, v2
	v_mov_b32_e32 v15, v2
	v_mov_b32_e32 v16, v2
	v_mov_b32_e32 v17, v2
	v_mov_b32_e32 v26, v2
	v_mov_b32_e32 v27, v2
	v_mov_b32_e32 v28, v2
	v_mov_b32_e32 v29, v2
	v_mov_b32_e32 v30, v2
	v_mov_b32_e32 v31, v2
	v_mov_b32_e32 v32, v2
	v_mov_b32_e32 v33, v2
	v_mov_b32_e32 v42, v2
	v_mov_b32_e32 v43, v2
	v_mov_b32_e32 v44, v2
	v_mov_b32_e32 v45, v2
	v_mov_b32_e32 v46, v2
	v_mov_b32_e32 v47, v2
	v_mov_b32_e32 v48, v2
	v_mov_b32_e32 v49, v2
	v_mov_b32_e32 v58, v2
	v_mov_b32_e32 v59, v2
	v_mov_b32_e32 v60, v2
	v_mov_b32_e32 v61, v2
	v_mov_b32_e32 v62, v2
	v_mov_b32_e32 v63, v2
	v_mov_b32_e32 v64, v2
	v_mov_b32_e32 v65, v2
	v_mov_b32_e32 v66, v2
	v_mov_b32_e32 v67, v2
	v_mov_b32_e32 v68, v2
	v_mov_b32_e32 v69, v2
	v_mov_b32_e32 v70, v2
	v_mov_b32_e32 v71, v2
	v_mov_b32_e32 v72, v2
	v_mov_b32_e32 v73, v2
	v_mov_b32_e32 v82, v2
	v_mov_b32_e32 v83, v2
	v_mov_b32_e32 v84, v2
	v_mov_b32_e32 v85, v2
	v_mov_b32_e32 v86, v2
	v_mov_b32_e32 v87, v2
	v_mov_b32_e32 v88, v2
	v_mov_b32_e32 v89, v2
	v_mov_b32_e32 v98, v2
	v_mov_b32_e32 v99, v2
	v_mov_b32_e32 v100, v2
	v_mov_b32_e32 v101, v2
	v_mov_b32_e32 v102, v2
	v_mov_b32_e32 v103, v2
	v_mov_b32_e32 v104, v2
	v_mov_b32_e32 v105, v2
	v_mov_b32_e32 v114, v2
	v_mov_b32_e32 v115, v2
	v_mov_b32_e32 v116, v2
	v_mov_b32_e32 v117, v2
	v_mov_b32_e32 v118, v2
	v_mov_b32_e32 v119, v2
	v_mov_b32_e32 v120, v2
	v_mov_b32_e32 v121, v2
	v_mov_b32_e32 v74, v2
	v_mov_b32_e32 v75, v2
	v_mov_b32_e32 v76, v2
	v_mov_b32_e32 v77, v2
	v_mov_b32_e32 v78, v2
	v_mov_b32_e32 v79, v2
	v_mov_b32_e32 v80, v2
	v_mov_b32_e32 v81, v2
	v_mov_b32_e32 v90, v2
	v_mov_b32_e32 v91, v2
	v_mov_b32_e32 v92, v2
	v_mov_b32_e32 v93, v2
	v_mov_b32_e32 v94, v2
	v_mov_b32_e32 v95, v2
	v_mov_b32_e32 v96, v2
	v_mov_b32_e32 v97, v2
	v_mov_b32_e32 v106, v2
	v_mov_b32_e32 v107, v2
	v_mov_b32_e32 v108, v2
	v_mov_b32_e32 v109, v2
	v_mov_b32_e32 v110, v2
	v_mov_b32_e32 v111, v2
	v_mov_b32_e32 v112, v2
	v_mov_b32_e32 v113, v2
	v_mov_b32_e32 v122, v2
	v_mov_b32_e32 v123, v2
	v_mov_b32_e32 v124, v2
	v_mov_b32_e32 v125, v2
	v_mov_b32_e32 v126, v2
	v_mov_b32_e32 v127, v2
	v_mov_b32_e32 v128, v2
	v_mov_b32_e32 v129, v2
	v_mov_b32_e32 v224, s52
	v_lshl_add_u32 v224, v224, 8, s65
	v_and_or_b32 v224, v252, 15, v224
	v_ashrrev_i32_e32 v225, 31, v224
	v_lshl_add_u64 v[226:227], v[224:225], 2, s[10:11]
	global_load_dword v232, v[226:227], off
	global_load_dword v233, v[226:227], off offset:64
	global_load_dword v234, v[226:227], off offset:128
	global_load_dword v235, v[226:227], off offset:192
	global_load_dword v236, v[226:227], off offset:512
	global_load_dword v237, v[226:227], off offset:576
	global_load_dword v238, v[226:227], off offset:640
	global_load_dword v239, v[226:227], off offset:704

; __device__ __forceinline__ unsigned cvt_pk_bf16(float lo, float hi) { unsigned r; asm volatile("v_cvt_pk_bf16_f32 %0, %1, %2" : "=v"(r) : "v"(lo), "v"(hi)); return r; }
;     __device__ __forceinline__ void operator()(const f32x4 (&acc)[2][2][4][2], const Unit& u, int wr, int wc, int fr_in, int fq_in) const {
;     ...
;         const float sc = (u.pn < 2 || u.pn == 6) ? qs : 1.0f;
;         float ssv[2][4];
; #pragma unroll
;         for (int ai = 0; ai < 2; ++ai)
; #pragma unroll
;             for (int m = 0; m < 4; ++m) ssv[ai][m] = SS[row0 + ai * HALF + m * 16];
; #pragma unroll
;         for (int ai = 0; ai < 2; ++ai)
; #pragma unroll
;             for (int m = 0; m < 4; ++m) {
;                 const int row = row0 + ai * HALF + m * 16;
;                 const float rs = __builtin_amdgcn_rsqf(ssv[ai][m] * (1.0f / 1024.0f) + 1e-6f) * sc;
;                 bf16_t* rowp = U + (size_t)row * DIN + col0;
; #pragma unroll
;                 for (int bj = 0; bj < 2; ++bj) {
;                     if (col0 + bj * HALF < DIN) {
;                         const f32x4 v0 = acc[ai][bj][m][0] * rs, v1 = acc[ai][bj][m][1] * rs;
;                         u32x4 w; w.x = cvt_pk_bf16(v0[0], v0[1]); w.y = cvt_pk_bf16(v0[2], v0[3]); w.z = cvt_pk_bf16(v1[0], v1[1]); w.w = cvt_pk_bf16(v1[2], v1[3]);
;                         *(u32x4*)(rowp + bj * HALF) = w;
.LBB0_550:
	s_lshl_b32 s5, s52, 8
	v_mov_b32_e32 v144, v252
	s_add_i32 s5, s5, s65
	s_nop 0
	v_and_or_b32 v140, v144, 15, s5
	v_ashrrev_i32_e32 v141, 31, v140
	v_lshl_add_u64 v[142:143], v[140:141], 2, s[10:11]
	s_lshl_b32 s5, s4, 8
	v_mov_b64_e32 v[142:143], s[16:17]
	v_lshrrev_b32_e32 v144, 1, v144
	s_cmp_eq_u32 s4, 6
	v_and_or_b32 v147, v144, 24, s5
	s_cselect_b64 s[36:37], -1, 0
	s_cmp_lt_i32 s4, 2
	v_mad_i64_i32 v[144:145], s[4:5], v140, s45, v[142:143]
	s_cselect_b64 s[4:5], -1, 0
	s_or_b64 vcc, s[4:5], s[36:37]
	v_or_b32_e32 v142, s69, v147
	s_movk_i32 s4, 0x9a0
	s_waitcnt lgkmcnt(0)
	v_fmamk_f32 v143, v232, 0x3a800000, v218
	v_rsq_f32_e32 v146, v143
	v_mov_b32_e32 v143, 0x3e38aa3b
	v_cndmask_b32_e32 v150, 1.0, v143, vcc
	v_ashrrev_i32_e32 v143, 31, v142
	v_mul_f32_e32 v146, v150, v146
	v_lshl_add_u64 v[144:145], v[142:143], 1, v[144:145]
	v_mov_b32_e32 v147, v146
	v_cmp_gt_i32_e32 vcc, s4, v142
	s_and_saveexec_b64 s[4:5], vcc
	v_readlane_b32 s60, v254, 49
	v_readlane_b32 s61, v254, 50
	s_cbranch_execz .LBB0_552
	v_mov_b32_e32 v158, v146
	v_mov_b32_e32 v159, v146
	v_pk_mul_f32 v[128:129], v[128:129], v[158:159]
	v_pk_mul_f32 v[158:159], v[124:125], v[158:159]
	v_pk_mul_f32 v[124:125], v[122:123], v[146:147]
	v_pk_mul_f32 v[126:127], v[126:127], v[146:147]
	s_nop 0
	v_cvt_pk_bf16_f32 v122, v126, v127
	v_cvt_pk_bf16_f32 v123, v128, v129
	v_cvt_pk_bf16_f32 v124, v124, v125
	v_cvt_pk_bf16_f32 v125, v158, v159
	flat_store_dwordx4 v[144:145], v[122:125]

; __device__ __forceinline__ unsigned cvt_pk_bf16(float lo, float hi) { unsigned r; asm volatile("v_cvt_pk_bf16_f32 %0, %1, %2" : "=v"(r) : "v"(lo), "v"(hi)); return r; }
;     __device__ __forceinline__ void operator()(const f32x4 (&acc)[2][2][4][2], const Unit& u, int wr, int wc, int fr_in, int fq_in) const {
;     ...
;         for (int ai = 0; ai < 2; ++ai)
; #pragma unroll
;             for (int m = 0; m < 4; ++m) {
;                 const int row = row0 + ai * HALF + m * 16;
;                 const float rs = __builtin_amdgcn_rsqf(ssv[ai][m] * (1.0f / 1024.0f) + 1e-6f) * sc;
;                 bf16_t* rowp = U + (size_t)row * DIN + col0;
; #pragma unroll
;                 for (int bj = 0; bj < 2; ++bj) {
;                     if (col0 + bj * HALF < DIN) {
;                         const f32x4 v0 = acc[ai][bj][m][0] * rs, v1 = acc[ai][bj][m][1] * rs;
;                         u32x4 w; w.x = cvt_pk_bf16(v0[0], v0[1]); w.y = cvt_pk_bf16(v0[2], v0[3]); w.z = cvt_pk_bf16(v1[0], v1[1]); w.w = cvt_pk_bf16(v1[2], v1[3]);
;                         *(u32x4*)(rowp + bj * HALF) = w;
.LBB0_554:
	s_or_b64 exec, exec, s[36:37]
	s_nop 0
	v_fmamk_f32 v114, v233, 0x3a800000, v218
	v_rsq_f32_e32 v116, v114
	v_or_b32_e32 v117, 16, v140
	v_mov_b64_e32 v[114:115], s[16:17]
	v_mad_i64_i32 v[114:115], s[36:37], v117, s45, v[114:115]
	v_mul_f32_e32 v116, v150, v116
	v_lshl_add_u64 v[114:115], v[142:143], 1, v[114:115]
	v_mov_b32_e32 v117, v116
	s_and_saveexec_b64 s[36:37], vcc
	s_cbranch_execz .LBB0_556
	v_mov_b32_e32 v118, v116
	v_mov_b32_e32 v119, v116
	v_pk_mul_f32 v[112:113], v[112:113], v[118:119]
	v_pk_mul_f32 v[118:119], v[108:109], v[118:119]
	v_pk_mul_f32 v[108:109], v[106:107], v[116:117]
	v_pk_mul_f32 v[110:111], v[110:111], v[116:117]
	s_nop 0
	v_cvt_pk_bf16_f32 v106, v110, v111
	v_cvt_pk_bf16_f32 v107, v112, v113
	v_cvt_pk_bf16_f32 v108, v108, v109
	v_cvt_pk_bf16_f32 v109, v118, v119
	flat_store_dwordx4 v[114:115], v[106:109]

; __device__ __forceinline__ unsigned cvt_pk_bf16(float lo, float hi) { unsigned r; asm volatile("v_cvt_pk_bf16_f32 %0, %1, %2" : "=v"(r) : "v"(lo), "v"(hi)); return r; }
;     __device__ __forceinline__ void operator()(const f32x4 (&acc)[2][2][4][2], const Unit& u, int wr, int wc, int fr_in, int fq_in) const {
;     ...
;         for (int ai = 0; ai < 2; ++ai)
; #pragma unroll
;             for (int m = 0; m < 4; ++m) {
;                 const int row = row0 + ai * HALF + m * 16;
;                 const float rs = __builtin_amdgcn_rsqf(ssv[ai][m] * (1.0f / 1024.0f) + 1e-6f) * sc;
;                 bf16_t* rowp = U + (size_t)row * DIN + col0;
; #pragma unroll
;                 for (int bj = 0; bj < 2; ++bj) {
;                     if (col0 + bj * HALF < DIN) {
;                         const f32x4 v0 = acc[ai][bj][m][0] * rs, v1 = acc[ai][bj][m][1] * rs;
;                         u32x4 w; w.x = cvt_pk_bf16(v0[0], v0[1]); w.y = cvt_pk_bf16(v0[2], v0[3]); w.z = cvt_pk_bf16(v1[0], v1[1]); w.w = cvt_pk_bf16(v1[2], v1[3]);
;                         *(u32x4*)(rowp + bj * HALF) = w;
.LBB0_558:
	s_or_b64 exec, exec, s[36:37]
	s_nop 0
	v_fmamk_f32 v98, v234, 0x3a800000, v218
	v_rsq_f32_e32 v100, v98
	v_or_b32_e32 v101, 32, v140
	v_mov_b64_e32 v[98:99], s[16:17]
	v_mad_i64_i32 v[98:99], s[36:37], v101, s45, v[98:99]
	v_mul_f32_e32 v100, v150, v100
	v_lshl_add_u64 v[98:99], v[142:143], 1, v[98:99]
	v_mov_b32_e32 v101, v100
	s_and_saveexec_b64 s[36:37], vcc
	s_cbranch_execz .LBB0_560
	v_mov_b32_e32 v102, v100
	v_mov_b32_e32 v103, v100
	v_pk_mul_f32 v[96:97], v[96:97], v[102:103]
	v_pk_mul_f32 v[102:103], v[92:93], v[102:103]
	v_pk_mul_f32 v[92:93], v[90:91], v[100:101]
	v_pk_mul_f32 v[94:95], v[94:95], v[100:101]
	s_nop 0
	v_cvt_pk_bf16_f32 v90, v94, v95
	v_cvt_pk_bf16_f32 v91, v96, v97
	v_cvt_pk_bf16_f32 v92, v92, v93
	v_cvt_pk_bf16_f32 v93, v102, v103
	flat_store_dwordx4 v[98:99], v[90:93]

; __device__ __forceinline__ unsigned cvt_pk_bf16(float lo, float hi) { unsigned r; asm volatile("v_cvt_pk_bf16_f32 %0, %1, %2" : "=v"(r) : "v"(lo), "v"(hi)); return r; }
;     __device__ __forceinline__ void operator()(const f32x4 (&acc)[2][2][4][2], const Unit& u, int wr, int wc, int fr_in, int fq_in) const {
;     ...
;         for (int ai = 0; ai < 2; ++ai)
; #pragma unroll
;             for (int m = 0; m < 4; ++m) {
;                 const int row = row0 + ai * HALF + m * 16;
;                 const float rs = __builtin_amdgcn_rsqf(ssv[ai][m] * (1.0f / 1024.0f) + 1e-6f) * sc;
;                 bf16_t* rowp = U + (size_t)row * DIN + col0;
; #pragma unroll
;                 for (int bj = 0; bj < 2; ++bj) {
;                     if (col0 + bj * HALF < DIN) {
;                         const f32x4 v0 = acc[ai][bj][m][0] * rs, v1 = acc[ai][bj][m][1] * rs;
;                         u32x4 w; w.x = cvt_pk_bf16(v0[0], v0[1]); w.y = cvt_pk_bf16(v0[2], v0[3]); w.z = cvt_pk_bf16(v1[0], v1[1]); w.w = cvt_pk_bf16(v1[2], v1[3]);
;                         *(u32x4*)(rowp + bj * HALF) = w;
.LBB0_562:
	s_or_b64 exec, exec, s[36:37]
	s_nop 0
	v_fmamk_f32 v82, v235, 0x3a800000, v218
	v_rsq_f32_e32 v84, v82
	v_or_b32_e32 v85, 48, v140
	v_mov_b64_e32 v[82:83], s[16:17]
	v_mad_i64_i32 v[82:83], s[36:37], v85, s45, v[82:83]
	v_mul_f32_e32 v84, v150, v84
	v_lshl_add_u64 v[82:83], v[142:143], 1, v[82:83]
	v_mov_b32_e32 v85, v84
	s_and_saveexec_b64 s[36:37], vcc
	s_cbranch_execz .LBB0_564
	v_mov_b32_e32 v86, v84
	v_mov_b32_e32 v87, v84
	v_pk_mul_f32 v[80:81], v[80:81], v[86:87]
	v_pk_mul_f32 v[86:87], v[76:77], v[86:87]
	v_pk_mul_f32 v[76:77], v[74:75], v[84:85]
	v_pk_mul_f32 v[78:79], v[78:79], v[84:85]
	s_nop 0
	v_cvt_pk_bf16_f32 v74, v78, v79
	v_cvt_pk_bf16_f32 v75, v80, v81
	v_cvt_pk_bf16_f32 v76, v76, v77
	v_cvt_pk_bf16_f32 v77, v86, v87
	flat_store_dwordx4 v[82:83], v[74:77]

; __device__ __forceinline__ unsigned cvt_pk_bf16(float lo, float hi) { unsigned r; asm volatile("v_cvt_pk_bf16_f32 %0, %1, %2" : "=v"(r) : "v"(lo), "v"(hi)); return r; }
;     __device__ __forceinline__ void operator()(const f32x4 (&acc)[2][2][4][2], const Unit& u, int wr, int wc, int fr_in, int fq_in) const {
;     ...
;         for (int ai = 0; ai < 2; ++ai)
; #pragma unroll
;             for (int m = 0; m < 4; ++m) {
;                 const int row = row0 + ai * HALF + m * 16;
;                 const float rs = __builtin_amdgcn_rsqf(ssv[ai][m] * (1.0f / 1024.0f) + 1e-6f) * sc;
;                 bf16_t* rowp = U + (size_t)row * DIN + col0;
; #pragma unroll
;                 for (int bj = 0; bj < 2; ++bj) {
;                     if (col0 + bj * HALF < DIN) {
;                         const f32x4 v0 = acc[ai][bj][m][0] * rs, v1 = acc[ai][bj][m][1] * rs;
;                         u32x4 w; w.x = cvt_pk_bf16(v0[0], v0[1]); w.y = cvt_pk_bf16(v0[2], v0[3]); w.z = cvt_pk_bf16(v1[0], v1[1]); w.w = cvt_pk_bf16(v1[2], v1[3]);
;                         *(u32x4*)(rowp + bj * HALF) = w;
.LBB0_566:
	s_or_b64 exec, exec, s[36:37]
	s_nop 0
	v_fmamk_f32 v66, v236, 0x3a800000, v218
	v_rsq_f32_e32 v68, v66
	v_add_u32_e32 v69, 0x80, v140
	v_mov_b64_e32 v[66:67], s[16:17]
	v_mad_i64_i32 v[66:67], s[36:37], v69, s45, v[66:67]
	v_mul_f32_e32 v68, v150, v68
	v_lshl_add_u64 v[66:67], v[142:143], 1, v[66:67]
	v_mov_b32_e32 v69, v68
	s_and_saveexec_b64 s[36:37], vcc
	s_cbranch_execz .LBB0_568
	v_mov_b32_e32 v70, v68
	v_mov_b32_e32 v71, v68
	v_pk_mul_f32 v[64:65], v[64:65], v[70:71]
	v_pk_mul_f32 v[70:71], v[60:61], v[70:71]
	v_pk_mul_f32 v[60:61], v[58:59], v[68:69]
	v_pk_mul_f32 v[62:63], v[62:63], v[68:69]
	s_nop 0
	v_cvt_pk_bf16_f32 v58, v62, v63
	v_cvt_pk_bf16_f32 v59, v64, v65
	v_cvt_pk_bf16_f32 v60, v60, v61
	v_cvt_pk_bf16_f32 v61, v70, v71
	flat_store_dwordx4 v[66:67], v[58:61]

; __device__ __forceinline__ unsigned cvt_pk_bf16(float lo, float hi) { unsigned r; asm volatile("v_cvt_pk_bf16_f32 %0, %1, %2" : "=v"(r) : "v"(lo), "v"(hi)); return r; }
;     __device__ __forceinline__ void operator()(const f32x4 (&acc)[2][2][4][2], const Unit& u, int wr, int wc, int fr_in, int fq_in) const {
;     ...
;         for (int ai = 0; ai < 2; ++ai)
; #pragma unroll
;             for (int m = 0; m < 4; ++m) {
;                 const int row = row0 + ai * HALF + m * 16;
;                 const float rs = __builtin_amdgcn_rsqf(ssv[ai][m] * (1.0f / 1024.0f) + 1e-6f) * sc;
;                 bf16_t* rowp = U + (size_t)row * DIN + col0;
; #pragma unroll
;                 for (int bj = 0; bj < 2; ++bj) {
;                     if (col0 + bj * HALF < DIN) {
;                         const f32x4 v0 = acc[ai][bj][m][0] * rs, v1 = acc[ai][bj][m][1] * rs;
;                         u32x4 w; w.x = cvt_pk_bf16(v0[0], v0[1]); w.y = cvt_pk_bf16(v0[2], v0[3]); w.z = cvt_pk_bf16(v1[0], v1[1]); w.w = cvt_pk_bf16(v1[2], v1[3]);
;                         *(u32x4*)(rowp + bj * HALF) = w;
.LBB0_570:
	s_or_b64 exec, exec, s[36:37]
	s_nop 0
	v_fmamk_f32 v50, v237, 0x3a800000, v218
	v_rsq_f32_e32 v52, v50
	v_add_u32_e32 v53, 0x90, v140
	v_mov_b64_e32 v[50:51], s[16:17]
	v_mad_i64_i32 v[50:51], s[36:37], v53, s45, v[50:51]
	v_mul_f32_e32 v52, v150, v52
	v_lshl_add_u64 v[50:51], v[142:143], 1, v[50:51]
	v_mov_b32_e32 v53, v52
	s_and_saveexec_b64 s[36:37], vcc
	s_cbranch_execz .LBB0_572
	v_mov_b32_e32 v54, v52
	v_mov_b32_e32 v55, v52
	v_pk_mul_f32 v[48:49], v[48:49], v[54:55]
	v_pk_mul_f32 v[54:55], v[44:45], v[54:55]
	v_pk_mul_f32 v[44:45], v[42:43], v[52:53]
	v_pk_mul_f32 v[46:47], v[46:47], v[52:53]
	s_nop 0
	v_cvt_pk_bf16_f32 v42, v46, v47
	v_cvt_pk_bf16_f32 v43, v48, v49
	v_cvt_pk_bf16_f32 v44, v44, v45
	v_cvt_pk_bf16_f32 v45, v54, v55
	flat_store_dwordx4 v[50:51], v[42:45]

; __device__ __forceinline__ unsigned cvt_pk_bf16(float lo, float hi) { unsigned r; asm volatile("v_cvt_pk_bf16_f32 %0, %1, %2" : "=v"(r) : "v"(lo), "v"(hi)); return r; }
;     __device__ __forceinline__ void operator()(const f32x4 (&acc)[2][2][4][2], const Unit& u, int wr, int wc, int fr_in, int fq_in) const {
;     ...
;         for (int ai = 0; ai < 2; ++ai)
; #pragma unroll
;             for (int m = 0; m < 4; ++m) {
;                 const int row = row0 + ai * HALF + m * 16;
;                 const float rs = __builtin_amdgcn_rsqf(ssv[ai][m] * (1.0f / 1024.0f) + 1e-6f) * sc;
;                 bf16_t* rowp = U + (size_t)row * DIN + col0;
; #pragma unroll
;                 for (int bj = 0; bj < 2; ++bj) {
;                     if (col0 + bj * HALF < DIN) {
;                         const f32x4 v0 = acc[ai][bj][m][0] * rs, v1 = acc[ai][bj][m][1] * rs;
;                         u32x4 w; w.x = cvt_pk_bf16(v0[0], v0[1]); w.y = cvt_pk_bf16(v0[2], v0[3]); w.z = cvt_pk_bf16(v1[0], v1[1]); w.w = cvt_pk_bf16(v1[2], v1[3]);
;                         *(u32x4*)(rowp + bj * HALF) = w;
.LBB0_574:
	s_or_b64 exec, exec, s[36:37]
	s_nop 0
	v_fmamk_f32 v34, v238, 0x3a800000, v218
	v_rsq_f32_e32 v36, v34
	v_add_u32_e32 v37, 0xa0, v140
	v_mov_b64_e32 v[34:35], s[16:17]
	v_mad_i64_i32 v[34:35], s[36:37], v37, s45, v[34:35]
	v_mul_f32_e32 v36, v150, v36
	v_lshl_add_u64 v[34:35], v[142:143], 1, v[34:35]
	v_mov_b32_e32 v37, v36
	s_and_saveexec_b64 s[36:37], vcc
	s_cbranch_execz .LBB0_576
	v_mov_b32_e32 v38, v36
	v_mov_b32_e32 v39, v36
	v_pk_mul_f32 v[32:33], v[32:33], v[38:39]
	v_pk_mul_f32 v[38:39], v[28:29], v[38:39]
	v_pk_mul_f32 v[28:29], v[26:27], v[36:37]
	v_pk_mul_f32 v[30:31], v[30:31], v[36:37]
	s_nop 0
	v_cvt_pk_bf16_f32 v26, v30, v31
	v_cvt_pk_bf16_f32 v27, v32, v33
	v_cvt_pk_bf16_f32 v28, v28, v29
	v_cvt_pk_bf16_f32 v29, v38, v39
	flat_store_dwordx4 v[34:35], v[26:29]

; __device__ __forceinline__ unsigned cvt_pk_bf16(float lo, float hi) { unsigned r; asm volatile("v_cvt_pk_bf16_f32 %0, %1, %2" : "=v"(r) : "v"(lo), "v"(hi)); return r; }
;     __device__ __forceinline__ void operator()(const f32x4 (&acc)[2][2][4][2], const Unit& u, int wr, int wc, int fr_in, int fq_in) const {
;     ...
;         for (int ai = 0; ai < 2; ++ai)
; #pragma unroll
;             for (int m = 0; m < 4; ++m) {
;                 const int row = row0 + ai * HALF + m * 16;
;                 const float rs = __builtin_amdgcn_rsqf(ssv[ai][m] * (1.0f / 1024.0f) + 1e-6f) * sc;
;                 bf16_t* rowp = U + (size_t)row * DIN + col0;
; #pragma unroll
;                 for (int bj = 0; bj < 2; ++bj) {
;                     if (col0 + bj * HALF < DIN) {
;                         const f32x4 v0 = acc[ai][bj][m][0] * rs, v1 = acc[ai][bj][m][1] * rs;
;                         u32x4 w; w.x = cvt_pk_bf16(v0[0], v0[1]); w.y = cvt_pk_bf16(v0[2], v0[3]); w.z = cvt_pk_bf16(v1[0], v1[1]); w.w = cvt_pk_bf16(v1[2], v1[3]);
;                         *(u32x4*)(rowp + bj * HALF) = w;
.LBB0_578:
	s_or_b64 exec, exec, s[36:37]
	s_nop 0
	v_fmamk_f32 v18, v239, 0x3a800000, v218
	v_rsq_f32_e32 v20, v18
	v_add_u32_e32 v21, 0xb0, v140
	v_mov_b64_e32 v[18:19], s[16:17]
	v_mad_i64_i32 v[18:19], s[36:37], v21, s45, v[18:19]
	v_mul_f32_e32 v20, v150, v20
	v_lshl_add_u64 v[18:19], v[142:143], 1, v[18:19]
	v_mov_b32_e32 v21, v20
	s_and_saveexec_b64 s[36:37], vcc
	s_cbranch_execnz .LBB0_581
	s_or_b64 exec, exec, s[36:37]
	s_and_saveexec_b64 s[36:37], s[4:5]
	s_cbranch_execnz .LBB0_582

; template <int MODE> __device__ __forceinline__ void attn_unit4(LAS unsigned char* lds, const int uidx, const AttnArgs& A) {
;     ...
;             const float sx = wave_sum(A.dl[lane] * A.dl[64 + lane], lane), sy = wave_sum(A.dl[128 + lane] * A.dl[192 + lane], lane);
;             const float lam = __expf(sx) - __expf(sy) + A.lam_init;
; __global__ void __launch_bounds__(NTHR, 2) mega_fwd(KArgs a) {
;     ...
;         {
;             AttnArgs A{U, KC, VC, (bf16_t*)(ws + WS_O), a.in[3], a.in[9] + (size_t)l * 256, a.in[10] + (size_t)l * 128, a.in[11] + (size_t)l * 4, 0.8f - 0.6f * __expf(-0.3f * (float)l)};
;             constexpr int NA = NSEQ * 4 * 65, NC = NSEQ * 2 * 65, NB = NSEQ * 2 * 65;
;             unsigned* qhead = (unsigned*)ws + CW_QUEUE + 64 * l;
.LBB0_907:
	s_or_b64 exec, exec, s[0:1]
	v_readlane_b32 s0, v254, 62
	s_add_u32 s10, s20, 0x2ea00000
	v_readlane_b32 s1, v254, 63
	v_readlane_b32 s68, v254, 33
	s_addc_u32 s11, s21, 0
	s_lshl_b64 s[0:1], s[0:1], 2
	v_readlane_b32 s76, v254, 41
	v_readlane_b32 s77, v254, 42
	s_add_u32 s0, s76, s0
	s_addc_u32 s1, s77, s1
	v_readlane_b32 s69, v254, 34
	v_readlane_b32 s70, v254, 35
	v_readlane_b32 s71, v254, 36
	v_readlane_b32 s72, v254, 37
	v_readlane_b32 s73, v254, 38
	v_readlane_b32 s74, v254, 39
	v_readlane_b32 s75, v254, 40
	v_readlane_b32 s78, v254, 43
	v_readlane_b32 s79, v254, 44
	v_readlane_b32 s80, v254, 45
	v_readlane_b32 s81, v254, 46
	v_readlane_b32 s82, v254, 47
	v_readlane_b32 s83, v254, 48
	v_writelane_b32 v254, s0, 62
	s_waitcnt lgkmcnt(0)
	v_mov_b32_e32 v2, 0x3f4ccccd
	v_writelane_b32 v254, s1, 63
	s_barrier
	v_readlane_b32 s0, v254, 59
	v_readlane_b32 s1, v254, 60
	v_readlane_b32 s4, v254, 55
	s_lshl_b64 s[0:1], s[0:1], 2
	v_readlane_b32 s5, v254, 56
	s_add_u32 s60, s78, s0
	v_cvt_f32_u32_e32 v0, s4
	s_addc_u32 s61, s79, s1
	s_lshl_b64 s[0:1], s[4:5], 4
	s_add_u32 s68, s80, s0
	s_addc_u32 s89, s81, s1
	s_lshl_b32 s30, s4, 6
	s_lshl_b64 s[0:1], s[30:31], 2
	v_mul_f32_e32 v0, 0xbe99999a, v0
	s_add_u32 s20, s20, s0
	v_mul_f32_e32 v0, 0x3fb8aa3b, v0
	s_addc_u32 s21, s21, s1
	v_exp_f32_e32 v0, v0
	s_cmp_eq_u32 s4, 1
	s_cselect_b64 s[82:83], -1, 0
	s_add_u32 s0, s16, 0x1000
	v_writelane_b32 v254, s0, 59
	s_addc_u32 s0, s17, 0
	v_writelane_b32 v255, s0, 0
	s_add_u32 s0, s16, 0x4df00
	v_fmamk_f32 v189, v0, 0xbf19999a, v2
	v_writelane_b32 v254, s0, 61
	s_addc_u32 s0, s17, 0
	v_sub_f32_e32 v191, 1.0, v189
	v_writelane_b32 v255, s0, 2
	v_readlane_b32 s84, v254, 62
	v_readlane_b32 s85, v254, 63
	v_and_b32_e32 v228, 63, v252
	v_lshlrev_b32_e32 v228, 2, v228
	s_nop 4
	global_load_dword v229, v228, s[84:85]
	global_load_dword v230, v228, s[84:85] offset:256
	global_load_dword v231, v228, s[84:85] offset:512
	global_load_dword v232, v228, s[84:85] offset:768
	s_waitcnt vmcnt(0)
	v_mul_f32_e32 v233, v229, v230
	v_xor_b32_e32 v234, 4, v228
	ds_bpermute_b32 v234, v234, v233
	s_waitcnt lgkmcnt(0)
	v_fmac_f32_e32 v234, v229, v230
	v_xor_b32_e32 v233, 8, v228
	ds_bpermute_b32 v233, v233, v234
	s_waitcnt lgkmcnt(0)
	v_add_f32_e32 v234, v234, v233
	v_xor_b32_e32 v233, 16, v228
	ds_bpermute_b32 v233, v233, v234
	s_waitcnt lgkmcnt(0)
	v_add_f32_e32 v234, v234, v233
	v_xor_b32_e32 v233, 32, v228
	ds_bpermute_b32 v233, v233, v234
	s_waitcnt lgkmcnt(0)
	v_add_f32_e32 v234, v234, v233
	v_xor_b32_e32 v233, 64, v228
	ds_bpermute_b32 v233, v233, v234
	s_waitcnt lgkmcnt(0)
	v_add_f32_e32 v234, v234, v233
	v_xor_b32_e32 v233, 0x80, v228
	ds_bpermute_b32 v233, v233, v234
	s_waitcnt lgkmcnt(0)
	v_add_f32_e32 v234, v234, v233
	v_mul_f32_e32 v234, 0x3fb8aa3b, v234
	v_exp_f32_e32 v235, v234
	v_mul_f32_e32 v233, v231, v232
	v_xor_b32_e32 v236, 4, v228
	ds_bpermute_b32 v236, v236, v233
	s_waitcnt lgkmcnt(0)
	v_fmac_f32_e32 v236, v231, v232
	v_xor_b32_e32 v233, 8, v228
	ds_bpermute_b32 v233, v233, v236
	s_waitcnt lgkmcnt(0)
	v_add_f32_e32 v236, v236, v233
	v_xor_b32_e32 v233, 16, v228
	ds_bpermute_b32 v233, v233, v236
	s_waitcnt lgkmcnt(0)
	v_add_f32_e32 v236, v236, v233
	v_xor_b32_e32 v233, 32, v228
	ds_bpermute_b32 v233, v233, v236
	s_waitcnt lgkmcnt(0)
	v_add_f32_e32 v236, v236, v233
	v_xor_b32_e32 v233, 64, v228
	ds_bpermute_b32 v233, v233, v236
	s_waitcnt lgkmcnt(0)
	v_add_f32_e32 v236, v236, v233
	v_xor_b32_e32 v233, 0x80, v228
	ds_bpermute_b32 v233, v233, v236
	s_waitcnt lgkmcnt(0)
	v_add_f32_e32 v236, v236, v233
	v_mul_f32_e32 v236, 0x3fb8aa3b, v236
	v_exp_f32_e32 v236, v236
	s_nop 0
	v_sub_f32_e32 v236, v235, v236
	v_add_f32_e32 v251, v189, v236
	s_branch .LBB0_912

; #define LAS __attribute__((address_space(3)))
; __device__ __forceinline__ float swapsum(float m) { auto rr = __builtin_amdgcn_permlane32_swap(__float_as_uint(m), __float_as_uint(m), false, false); return __uint_as_float(rr[0]) + __uint_as_float(rr[1]); }
; template <int MODE> __device__ __forceinline__ void attn_unit4(LAS unsigned char* lds, const int uidx, const AttnArgs& A) {
;     ...
;     if (MODE == 0) {
;         LAS float* X = (LAS float*)lds;
;         if (st == 1) {
; #pragma unroll
;             for (int d = 0; d < NDB; ++d)
; #pragma unroll
;                 for (int r = 0; r < 16; ++r) X[(qg * 64 + d * 16 + r) * 64 + lane] = o[d][r];
;         }
;         __syncthreads();
;         if (st == 0) {
;             const float sx = wave_sum(A.dl[lane] * A.dl[64 + lane], lane), sy = wave_sum(A.dl[128 + lane] * A.dl[192 + lane], lane);
;             const float lam = __expf(sx) - __expf(sy) + A.lam_init;
;             float ss = 0.f;
; #pragma unroll
;             for (int d = 0; d < NDB; ++d)
; #pragma unroll
;                 for (int r = 0; r < 16; ++r) { const float v = o[d][r] - lam * X[(qg * 64 + d * 16 + r) * 64 + lane]; o[d][r] = v; ss += v * v; }
;             ss = swapsum(ss);
;             const float rs = (1.0f / sqrtf(ss * (1.0f / 128.0f) + EPSN)) * (1.0f - A.lam_init);
.LBB0_1005:
	s_cmpk_gt_u32 s30, 0xff
	s_waitcnt lgkmcnt(0)
	s_barrier
	s_cbranch_scc1 .LBB0_908
	v_lshlrev_b32_e32 v0, 2, v177
	s_lshl_b32 s0, s30, 8
	v_add_u32_e32 v0, 0, v0
	s_and_b32 s1, s0, 0xc000
	s_or_b32 s0, s0, 0x3f00
	v_mov_b32_e32 v14, v251
	v_add_u32_e32 v4, s1, v0
	v_add_u32_e32 v0, s0, v0
	ds_read2st64_b32 v[132:133], v4 offset1:1
	ds_read2st64_b32 v[134:135], v4 offset0:2 offset1:3
	ds_read2st64_b32 v[128:129], v4 offset0:4 offset1:5
	ds_read2st64_b32 v[130:131], v4 offset0:6 offset1:7
	ds_read2st64_b32 v[124:125], v4 offset0:8 offset1:9
	ds_read2st64_b32 v[126:127], v4 offset0:10 offset1:11
	ds_read2st64_b32 v[120:121], v4 offset0:12 offset1:13
	ds_read2st64_b32 v[122:123], v4 offset0:14 offset1:15
	ds_read2st64_b32 v[116:117], v4 offset0:16 offset1:17
	ds_read2st64_b32 v[118:119], v4 offset0:18 offset1:19
	ds_read2st64_b32 v[112:113], v4 offset0:20 offset1:21
	ds_read2st64_b32 v[114:115], v4 offset0:22 offset1:23
	ds_read2st64_b32 v[108:109], v4 offset0:24 offset1:25
	ds_read2st64_b32 v[110:111], v4 offset0:26 offset1:27
	ds_read2st64_b32 v[104:105], v4 offset0:28 offset1:29
	ds_read2st64_b32 v[106:107], v4 offset0:30 offset1:31
	ds_read2st64_b32 v[100:101], v4 offset0:32 offset1:33
	ds_read2st64_b32 v[102:103], v4 offset0:34 offset1:35
	ds_read2st64_b32 v[96:97], v4 offset0:36 offset1:37
	ds_read2st64_b32 v[98:99], v4 offset0:38 offset1:39
	ds_read2st64_b32 v[92:93], v4 offset0:40 offset1:41
	ds_read2st64_b32 v[94:95], v4 offset0:42 offset1:43
	ds_read2st64_b32 v[56:57], v4 offset0:44 offset1:45
	ds_read2st64_b32 v[58:59], v4 offset0:46 offset1:47
	ds_read2st64_b32 v[50:51], v4 offset0:48 offset1:49
	ds_read2st64_b32 v[52:53], v4 offset0:50 offset1:51
	ds_read2st64_b32 v[44:45], v4 offset0:52 offset1:53
	ds_read2st64_b32 v[46:47], v4 offset0:54 offset1:55
	ds_read2st64_b32 v[32:33], v4 offset0:56 offset1:57
	ds_read2st64_b32 v[42:43], v4 offset0:58 offset1:59
	ds_read2st64_b32 v[16:17], v4 offset0:60 offset1:61
	ds_read_b32 v4, v4 offset:15872
	ds_read_b32 v5, v0
	v_lshlrev_b32_e32 v0, 1, v181
	s_mov_b32 s0, 0xf800000
	s_waitcnt lgkmcnt(0)
	v_pk_fma_f32 v[8:9], v[14:15], v[4:5], v[2:3] op_sel_hi:[0,1,1] neg_lo:[1,0,0] neg_hi:[1,0,0]
	v_lshlrev_b64 v[2:3], 11, v[166:167]
	v_lshl_add_u64 v[2:3], s[10:11], 0, v[2:3]
	v_lshlrev_b32_e32 v15, 2, v181
	v_lshl_add_u64 v[2:3], s[26:27], 1, v[2:3]
	v_pk_fma_f32 v[88:89], v[132:133], v[14:15], v[88:89] op_sel_hi:[1,0,1] neg_lo:[1,0,0] neg_hi:[1,0,0]
	v_lshl_add_u64 v[6:7], v[2:3], 0, v[0:1]
	v_mul_f32_e32 v0, v89, v89
	v_pk_fma_f32 v[90:91], v[134:135], v[14:15], v[90:91] op_sel_hi:[1,0,1] neg_lo:[1,0,0] neg_hi:[1,0,0]
	v_pk_fma_f32 v[132:133], v[88:89], v[88:89], v[0:1] op_sel_hi:[1,1,0]
	v_mul_f32_e32 v0, v91, v91
	v_pk_fma_f32 v[132:133], v[90:91], v[90:91], v[132:133]
	v_pk_fma_f32 v[84:85], v[128:129], v[14:15], v[84:85] op_sel_hi:[1,0,1] neg_lo:[1,0,0] neg_hi:[1,0,0]
	v_pk_add_f32 v[132:133], v[0:1], v[132:133] op_sel_hi:[0,1]
	v_pk_fma_f32 v[128:129], v[84:85], v[84:85], v[132:133]
	v_mul_f32_e32 v0, v85, v85
	v_pk_fma_f32 v[86:87], v[14:15], v[130:131], v[86:87] op_sel_hi:[0,1,1] neg_lo:[1,0,0] neg_hi:[1,0,0]
	v_pk_add_f32 v[128:129], v[0:1], v[128:129] op_sel_hi:[0,1]
	v_pk_fma_f32 v[128:129], v[86:87], v[86:87], v[128:129]
	v_mul_f32_e32 v0, v87, v87
	v_pk_add_f32 v[128:129], v[0:1], v[128:129] op_sel_hi:[0,1]
	v_pk_fma_f32 v[80:81], v[14:15], v[124:125], v[80:81] op_sel_hi:[0,1,1] neg_lo:[1,0,0] neg_hi:[1,0,0]
	v_pk_fma_f32 v[124:125], v[80:81], v[80:81], v[128:129]
	v_mul_f32_e32 v0, v81, v81
	v_pk_fma_f32 v[82:83], v[14:15], v[126:127], v[82:83] op_sel_hi:[0,1,1] neg_lo:[1,0,0] neg_hi:[1,0,0]
	v_pk_add_f32 v[124:125], v[0:1], v[124:125] op_sel_hi:[0,1]
	v_pk_fma_f32 v[124:125], v[82:83], v[82:83], v[124:125]
	v_mul_f32_e32 v0, v83, v83
	v_pk_add_f32 v[124:125], v[0:1], v[124:125] op_sel_hi:[0,1]
	v_pk_fma_f32 v[76:77], v[14:15], v[120:121], v[76:77] op_sel_hi:[0,1,1] neg_lo:[1,0,0] neg_hi:[1,0,0]
	v_pk_fma_f32 v[120:121], v[76:77], v[76:77], v[124:125]
	v_mul_f32_e32 v0, v77, v77
	v_pk_fma_f32 v[78:79], v[14:15], v[122:123], v[78:79] op_sel_hi:[0,1,1] neg_lo:[1,0,0] neg_hi:[1,0,0]
	v_pk_add_f32 v[120:121], v[0:1], v[120:121] op_sel_hi:[0,1]
	v_pk_fma_f32 v[120:121], v[78:79], v[78:79], v[120:121]
	v_mul_f32_e32 v0, v79, v79
	v_pk_add_f32 v[120:121], v[0:1], v[120:121] op_sel_hi:[0,1]
	v_pk_fma_f32 v[72:73], v[14:15], v[116:117], v[72:73] op_sel_hi:[0,1,1] neg_lo:[1,0,0] neg_hi:[1,0,0]
	v_pk_fma_f32 v[116:117], v[72:73], v[72:73], v[120:121]
	v_mul_f32_e32 v0, v73, v73
	v_pk_fma_f32 v[74:75], v[14:15], v[118:119], v[74:75] op_sel_hi:[0,1,1] neg_lo:[1,0,0] neg_hi:[1,0,0]
	v_pk_add_f32 v[116:117], v[0:1], v[116:117] op_sel_hi:[0,1]
	v_pk_fma_f32 v[116:117], v[74:75], v[74:75], v[116:117]
	v_mul_f32_e32 v0, v75, v75
	global_load_dwordx4 v[2:5], v15, s[60:61]
	v_pk_add_f32 v[116:117], v[0:1], v[116:117] op_sel_hi:[0,1]
	v_pk_fma_f32 v[68:69], v[14:15], v[112:113], v[68:69] op_sel_hi:[0,1,1] neg_lo:[1,0,0] neg_hi:[1,0,0]
	v_pk_fma_f32 v[112:113], v[68:69], v[68:69], v[116:117]
	v_mul_f32_e32 v0, v69, v69
	v_pk_fma_f32 v[70:71], v[14:15], v[114:115], v[70:71] op_sel_hi:[0,1,1] neg_lo:[1,0,0] neg_hi:[1,0,0]
	v_pk_add_f32 v[112:113], v[0:1], v[112:113] op_sel_hi:[0,1]
	v_pk_fma_f32 v[112:113], v[70:71], v[70:71], v[112:113]
	v_mul_f32_e32 v0, v71, v71
	v_pk_add_f32 v[112:113], v[0:1], v[112:113] op_sel_hi:[0,1]
	v_pk_fma_f32 v[64:65], v[14:15], v[108:109], v[64:65] op_sel_hi:[0,1,1] neg_lo:[1,0,0] neg_hi:[1,0,0]
	v_pk_fma_f32 v[108:109], v[64:65], v[64:65], v[112:113]
	v_mul_f32_e32 v0, v65, v65
	v_pk_fma_f32 v[66:67], v[14:15], v[110:111], v[66:67] op_sel_hi:[0,1,1] neg_lo:[1,0,0] neg_hi:[1,0,0]
; __device__ __forceinline__ float swapsum(float m) { auto rr = __builtin_amdgcn_permlane32_swap(__float_as_uint(m), __float_as_uint(m), false, false); return __uint_as_float(rr[0]) + __uint_as_float(rr[1]); }
; template <int MODE> __device__ __forceinline__ void attn_unit4(LAS unsigned char* lds, const int uidx, const AttnArgs& A) {
;     ...
;             for (int d = 0; d < NDB; ++d)
; #pragma unroll
;                 for (int r = 0; r < 16; ++r) { const float v = o[d][r] - lam * X[(qg * 64 + d * 16 + r) * 64 + lane]; o[d][r] = v; ss += v * v; }
;             ss = swapsum(ss);
;             const float rs = (1.0f / sqrtf(ss * (1.0f / 128.0f) + EPSN)) * (1.0f - A.lam_init);
	v_pk_add_f32 v[108:109], v[0:1], v[108:109] op_sel_hi:[0,1]
	v_pk_fma_f32 v[108:109], v[66:67], v[66:67], v[108:109]
	v_mul_f32_e32 v0, v67, v67
	v_pk_add_f32 v[108:109], v[0:1], v[108:109] op_sel_hi:[0,1]
	v_pk_fma_f32 v[60:61], v[14:15], v[104:105], v[60:61] op_sel_hi:[0,1,1] neg_lo:[1,0,0] neg_hi:[1,0,0]
	v_pk_fma_f32 v[104:105], v[60:61], v[60:61], v[108:109]
	v_mul_f32_e32 v0, v61, v61
	v_pk_fma_f32 v[62:63], v[14:15], v[106:107], v[62:63] op_sel_hi:[0,1,1] neg_lo:[1,0,0] neg_hi:[1,0,0]
	v_pk_add_f32 v[104:105], v[0:1], v[104:105] op_sel_hi:[0,1]
	v_pk_fma_f32 v[104:105], v[62:63], v[62:63], v[104:105]
	v_mul_f32_e32 v0, v63, v63
	v_pk_add_f32 v[104:105], v[0:1], v[104:105] op_sel_hi:[0,1]
	v_pk_fma_f32 v[48:49], v[14:15], v[100:101], v[48:49] op_sel_hi:[0,1,1] neg_lo:[1,0,0] neg_hi:[1,0,0]
	v_pk_fma_f32 v[100:101], v[48:49], v[48:49], v[104:105]
	v_mul_f32_e32 v0, v49, v49
	v_pk_fma_f32 v[54:55], v[14:15], v[102:103], v[54:55] op_sel_hi:[0,1,1] neg_lo:[1,0,0] neg_hi:[1,0,0]
	v_pk_add_f32 v[100:101], v[0:1], v[100:101] op_sel_hi:[0,1]
	v_pk_fma_f32 v[100:101], v[54:55], v[54:55], v[100:101]
	v_mul_f32_e32 v0, v55, v55
	v_pk_add_f32 v[100:101], v[0:1], v[100:101] op_sel_hi:[0,1]
	v_pk_fma_f32 v[38:39], v[14:15], v[96:97], v[38:39] op_sel_hi:[0,1,1] neg_lo:[1,0,0] neg_hi:[1,0,0]
	v_pk_fma_f32 v[96:97], v[38:39], v[38:39], v[100:101]
	v_mul_f32_e32 v0, v39, v39
	v_pk_fma_f32 v[40:41], v[14:15], v[98:99], v[40:41] op_sel_hi:[0,1,1] neg_lo:[1,0,0] neg_hi:[1,0,0]
	v_pk_add_f32 v[96:97], v[0:1], v[96:97] op_sel_hi:[0,1]
	v_pk_fma_f32 v[96:97], v[40:41], v[40:41], v[96:97]
	v_mul_f32_e32 v0, v41, v41
	v_pk_add_f32 v[96:97], v[0:1], v[96:97] op_sel_hi:[0,1]
	v_pk_fma_f32 v[34:35], v[14:15], v[92:93], v[34:35] op_sel_hi:[0,1,1] neg_lo:[1,0,0] neg_hi:[1,0,0]
	v_pk_fma_f32 v[92:93], v[34:35], v[34:35], v[96:97]
	v_mul_f32_e32 v0, v35, v35
	v_pk_fma_f32 v[36:37], v[14:15], v[94:95], v[36:37] op_sel_hi:[0,1,1] neg_lo:[1,0,0] neg_hi:[1,0,0]
	v_pk_add_f32 v[92:93], v[0:1], v[92:93] op_sel_hi:[0,1]
	v_pk_fma_f32 v[92:93], v[36:37], v[36:37], v[92:93]
	v_mul_f32_e32 v0, v37, v37
	v_pk_add_f32 v[92:93], v[0:1], v[92:93] op_sel_hi:[0,1]
	v_pk_fma_f32 v[56:57], v[14:15], v[56:57], v[26:27] op_sel_hi:[0,1,1] neg_lo:[1,0,0] neg_hi:[1,0,0]
	v_pk_fma_f32 v[26:27], v[56:57], v[56:57], v[92:93]
	v_mul_f32_e32 v0, v57, v57
	v_pk_fma_f32 v[30:31], v[14:15], v[58:59], v[30:31] op_sel_hi:[0,1,1] neg_lo:[1,0,0] neg_hi:[1,0,0]
	v_pk_add_f32 v[26:27], v[0:1], v[26:27] op_sel_hi:[0,1]
	v_pk_fma_f32 v[26:27], v[30:31], v[30:31], v[26:27]
	v_mul_f32_e32 v0, v31, v31
	v_pk_add_f32 v[58:59], v[0:1], v[26:27] op_sel_hi:[0,1]
	v_pk_fma_f32 v[24:25], v[14:15], v[50:51], v[24:25] op_sel_hi:[0,1,1] neg_lo:[1,0,0] neg_hi:[1,0,0]
	v_pk_fma_f32 v[26:27], v[14:15], v[52:53], v[28:29] op_sel_hi:[0,1,1] neg_lo:[1,0,0] neg_hi:[1,0,0]
	v_pk_fma_f32 v[28:29], v[24:25], v[24:25], v[58:59]
	v_mul_f32_e32 v0, v25, v25
	v_pk_add_f32 v[28:29], v[0:1], v[28:29] op_sel_hi:[0,1]
	v_pk_fma_f32 v[28:29], v[26:27], v[26:27], v[28:29]
	v_mul_f32_e32 v0, v27, v27
	v_pk_add_f32 v[28:29], v[0:1], v[28:29] op_sel_hi:[0,1]
	v_pk_fma_f32 v[20:21], v[14:15], v[44:45], v[20:21] op_sel_hi:[0,1,1] neg_lo:[1,0,0] neg_hi:[1,0,0]
	v_pk_fma_f32 v[28:29], v[20:21], v[20:21], v[28:29]
	v_mul_f32_e32 v0, v21, v21
	v_pk_fma_f32 v[22:23], v[14:15], v[46:47], v[22:23] op_sel_hi:[0,1,1] neg_lo:[1,0,0] neg_hi:[1,0,0]
	v_pk_add_f32 v[28:29], v[0:1], v[28:29] op_sel_hi:[0,1]
	v_pk_fma_f32 v[28:29], v[22:23], v[22:23], v[28:29]
	v_mul_f32_e32 v0, v23, v23
	v_pk_add_f32 v[28:29], v[0:1], v[28:29] op_sel_hi:[0,1]
	v_pk_fma_f32 v[18:19], v[14:15], v[32:33], v[18:19] op_sel_hi:[0,1,1] neg_lo:[1,0,0] neg_hi:[1,0,0]
	v_pk_fma_f32 v[28:29], v[18:19], v[18:19], v[28:29]
	v_mul_f32_e32 v0, v19, v19
	v_pk_fma_f32 v[12:13], v[14:15], v[42:43], v[12:13] op_sel_hi:[0,1,1] neg_lo:[1,0,0] neg_hi:[1,0,0]
	v_pk_add_f32 v[28:29], v[0:1], v[28:29] op_sel_hi:[0,1]
	v_pk_fma_f32 v[28:29], v[12:13], v[12:13], v[28:29]
	v_mul_f32_e32 v0, v13, v13
	v_pk_add_f32 v[28:29], v[0:1], v[28:29] op_sel_hi:[0,1]
	v_pk_fma_f32 v[10:11], v[14:15], v[16:17], v[10:11] op_sel_hi:[0,1,1] neg_lo:[1,0,0] neg_hi:[1,0,0]
	v_pk_fma_f32 v[16:17], v[10:11], v[10:11], v[28:29]
	v_mul_f32_e32 v0, v11, v11
	v_pk_add_f32 v[16:17], v[0:1], v[16:17] op_sel_hi:[0,1]
	v_pk_fma_f32 v[16:17], v[8:9], v[8:9], v[16:17]
	v_mul_f32_e32 v0, v9, v9
	v_pk_add_f32 v[16:17], v[0:1], v[16:17] op_sel_hi:[0,1]
	v_mov_b32_e32 v0, v16
	s_nop 1
	v_permlane32_swap_b32_e32 v16, v0
	v_add_f32_e32 v0, v16, v0
	v_fmamk_f32 v0, v0, 0x3c000000, v218
	v_cmp_gt_f32_e32 vcc, s0, v0
	v_mul_f32_e32 v14, 0x4f800000, v0
	s_nop 0
	v_cndmask_b32_e32 v0, v0, v14, vcc
	v_sqrt_f32_e32 v14, v0
	s_nop 0
	v_add_u32_e32 v16, -1, v14
	v_fma_f32 v17, -v16, v14, v0
	v_cmp_ge_f32_e64 s[0:1], 0, v17
	v_add_u32_e32 v17, 1, v14
	s_nop 0
	v_cndmask_b32_e64 v16, v14, v16, s[0:1]
	v_fma_f32 v14, -v17, v14, v0
	v_cmp_lt_f32_e64 s[0:1], 0, v14
	s_nop 1
	v_cndmask_b32_e64 v14, v16, v17, s[0:1]
	v_mul_f32_e32 v16, 0x37800000, v14
	v_cndmask_b32_e32 v14, v14, v16, vcc
	v_mov_b32_e32 v16, 0x260
	v_cmp_class_f32_e32 vcc, v0, v16
	s_nop 1
	v_cndmask_b32_e32 v0, v14, v0, vcc
	v_div_scale_f32 v14, s[0:1], v0, v0, 1.0
	v_rcp_f32_e32 v16, v14
	s_nop 0
	v_fma_f32 v17, -v14, v16, 1.0
	v_fmac_f32_e32 v16, v17, v16
	v_div_scale_f32 v17, vcc, 1.0, v0, 1.0
	v_mul_f32_e32 v28, v17, v16
	v_fma_f32 v29, -v14, v28, v17
	v_fmac_f32_e32 v28, v29, v16
	v_fma_f32 v14, -v14, v28, v17
	v_div_fmas_f32 v14, v14, v16, v28
	v_div_fixup_f32 v0, v14, v0, 1.0
	v_mul_f32_e32 v0, v191, v0
	v_pk_mul_f32 v[16:17], v[88:89], v[0:1] op_sel_hi:[1,0]
	v_pk_mul_f32 v[12:13], v[12:13], v[0:1] op_sel_hi:[1,0]
	s_waitcnt vmcnt(0)
; #define GAS __attribute__((address_space(1)))
; __device__ __forceinline__ unsigned cvtpk(float lo, float hi) { f32x2_t v = {lo, hi}; bf16x2_t b = __builtin_convertvector(v, bf16x2_t); return __builtin_bit_cast(unsigned, b); }
; template <int MODE> __device__ __forceinline__ void attn_unit4(LAS unsigned char* lds, const int uidx, const AttnArgs& A) {
;     ...
;             GAS bf16_t* op = (GAS bf16_t*)A.O + orow * DM + hx * 128 + 4 * hi;
; #pragma unroll
;             for (int d = 0; d < NDB; ++d)
; #pragma unroll
;                 for (int g4 = 0; g4 < 4; ++g4) {
;                     const f32x4 gv = *(const GAS f32x4*)((const GAS float*)A.gsub + d * 32 + 8 * g4 + 4 * hi);
;                     u32x2 w; w.x = cvtpk(o[d][4 * g4] * rs * gv[0], o[d][4 * g4 + 1] * rs * gv[1]); w.y = cvtpk(o[d][4 * g4 + 2] * rs * gv[2], o[d][4 * g4 + 3] * rs * gv[3]);
;                     *(GAS u32x2*)(op + d * 32 + 8 * g4) = w;
;                 }
	v_pk_mul_f32 v[2:3], v[2:3], v[16:17]
	v_pk_mul_f32 v[16:17], v[90:91], v[0:1] op_sel_hi:[1,0]
	v_cvt_pk_bf16_f32 v2, v2, v3
	v_pk_mul_f32 v[4:5], v[4:5], v[16:17]
	v_pk_mul_f32 v[16:17], v[84:85], v[0:1] op_sel_hi:[1,0]
	v_cvt_pk_bf16_f32 v3, v4, v5
	global_store_dwordx2 v[6:7], v[2:3], off
	global_load_dwordx4 v[2:5], v15, s[60:61] offset:32
	v_pk_mul_f32 v[10:11], v[10:11], v[0:1] op_sel_hi:[1,0]
	v_pk_mul_f32 v[8:9], v[8:9], v[0:1] op_sel_hi:[1,0]
	s_waitcnt vmcnt(0)
	v_pk_mul_f32 v[2:3], v[2:3], v[16:17]
	v_pk_mul_f32 v[16:17], v[86:87], v[0:1] op_sel_hi:[1,0]
	v_cvt_pk_bf16_f32 v2, v2, v3
	v_pk_mul_f32 v[4:5], v[4:5], v[16:17]
	v_pk_mul_f32 v[16:17], v[80:81], v[0:1] op_sel_hi:[1,0]
	v_cvt_pk_bf16_f32 v3, v4, v5
	global_store_dwordx2 v[6:7], v[2:3], off offset:16
	global_load_dwordx4 v[2:5], v15, s[60:61] offset:64
	s_waitcnt vmcnt(0)
	v_pk_mul_f32 v[2:3], v[2:3], v[16:17]
	v_pk_mul_f32 v[16:17], v[82:83], v[0:1] op_sel_hi:[1,0]
	v_cvt_pk_bf16_f32 v2, v2, v3
	v_pk_mul_f32 v[4:5], v[4:5], v[16:17]
	v_pk_mul_f32 v[16:17], v[76:77], v[0:1] op_sel_hi:[1,0]
	v_cvt_pk_bf16_f32 v3, v4, v5
	global_store_dwordx2 v[6:7], v[2:3], off offset:32
	global_load_dwordx4 v[2:5], v15, s[60:61] offset:96
	s_waitcnt vmcnt(0)
	v_pk_mul_f32 v[2:3], v[2:3], v[16:17]
	v_pk_mul_f32 v[16:17], v[78:79], v[0:1] op_sel_hi:[1,0]
	v_cvt_pk_bf16_f32 v2, v2, v3
	v_pk_mul_f32 v[4:5], v[4:5], v[16:17]
	v_pk_mul_f32 v[16:17], v[72:73], v[0:1] op_sel_hi:[1,0]
	v_cvt_pk_bf16_f32 v3, v4, v5
	global_store_dwordx2 v[6:7], v[2:3], off offset:48
	global_load_dwordx4 v[2:5], v15, s[60:61] offset:128
	s_waitcnt vmcnt(0)
	v_pk_mul_f32 v[2:3], v[16:17], v[2:3]
	v_pk_mul_f32 v[16:17], v[74:75], v[0:1] op_sel_hi:[1,0]
	v_cvt_pk_bf16_f32 v2, v2, v3
	v_pk_mul_f32 v[4:5], v[16:17], v[4:5]
	v_pk_mul_f32 v[16:17], v[68:69], v[0:1] op_sel_hi:[1,0]
	v_cvt_pk_bf16_f32 v3, v4, v5
	global_store_dwordx2 v[6:7], v[2:3], off offset:64
	global_load_dwordx4 v[2:5], v15, s[60:61] offset:160
	s_waitcnt vmcnt(0)
	v_pk_mul_f32 v[2:3], v[16:17], v[2:3]
	v_pk_mul_f32 v[16:17], v[70:71], v[0:1] op_sel_hi:[1,0]
	v_cvt_pk_bf16_f32 v2, v2, v3
	v_pk_mul_f32 v[4:5], v[16:17], v[4:5]
	v_pk_mul_f32 v[16:17], v[64:65], v[0:1] op_sel_hi:[1,0]
	v_cvt_pk_bf16_f32 v3, v4, v5
	global_store_dwordx2 v[6:7], v[2:3], off offset:80
	global_load_dwordx4 v[2:5], v15, s[60:61] offset:192
	s_waitcnt vmcnt(0)
	v_pk_mul_f32 v[2:3], v[16:17], v[2:3]
	v_pk_mul_f32 v[16:17], v[66:67], v[0:1] op_sel_hi:[1,0]
	v_cvt_pk_bf16_f32 v2, v2, v3
	v_pk_mul_f32 v[4:5], v[16:17], v[4:5]
	v_pk_mul_f32 v[16:17], v[60:61], v[0:1] op_sel_hi:[1,0]
	v_cvt_pk_bf16_f32 v3, v4, v5
	global_store_dwordx2 v[6:7], v[2:3], off offset:96
	global_load_dwordx4 v[2:5], v15, s[60:61] offset:224
	s_waitcnt vmcnt(0)
	v_pk_mul_f32 v[2:3], v[16:17], v[2:3]
	v_pk_mul_f32 v[16:17], v[62:63], v[0:1] op_sel_hi:[1,0]
	v_cvt_pk_bf16_f32 v2, v2, v3
	v_pk_mul_f32 v[4:5], v[16:17], v[4:5]
	v_pk_mul_f32 v[16:17], v[48:49], v[0:1] op_sel_hi:[1,0]
	v_cvt_pk_bf16_f32 v3, v4, v5
	global_store_dwordx2 v[6:7], v[2:3], off offset:112
	global_load_dwordx4 v[2:5], v15, s[60:61] offset:256
	s_waitcnt vmcnt(0)
	v_pk_mul_f32 v[2:3], v[16:17], v[2:3]
	v_pk_mul_f32 v[16:17], v[54:55], v[0:1] op_sel_hi:[1,0]
	v_cvt_pk_bf16_f32 v2, v2, v3
	v_pk_mul_f32 v[4:5], v[16:17], v[4:5]
	v_pk_mul_f32 v[16:17], v[38:39], v[0:1] op_sel_hi:[1,0]
	v_cvt_pk_bf16_f32 v3, v4, v5
	global_store_dwordx2 v[6:7], v[2:3], off offset:128
	global_load_dwordx4 v[2:5], v15, s[60:61] offset:288
	s_waitcnt vmcnt(0)
	v_pk_mul_f32 v[2:3], v[16:17], v[2:3]
	v_pk_mul_f32 v[16:17], v[40:41], v[0:1] op_sel_hi:[1,0]
	v_cvt_pk_bf16_f32 v2, v2, v3
	v_pk_mul_f32 v[4:5], v[16:17], v[4:5]
	v_pk_mul_f32 v[16:17], v[34:35], v[0:1] op_sel_hi:[1,0]
	v_cvt_pk_bf16_f32 v3, v4, v5
	global_store_dwordx2 v[6:7], v[2:3], off offset:144
	global_load_dwordx4 v[2:5], v15, s[60:61] offset:320
	s_waitcnt vmcnt(0)
	v_pk_mul_f32 v[2:3], v[16:17], v[2:3]
	v_pk_mul_f32 v[16:17], v[36:37], v[0:1] op_sel_hi:[1,0]
	v_cvt_pk_bf16_f32 v2, v2, v3
	v_pk_mul_f32 v[4:5], v[16:17], v[4:5]
	v_pk_mul_f32 v[16:17], v[56:57], v[0:1] op_sel_hi:[1,0]
	v_cvt_pk_bf16_f32 v3, v4, v5
	global_store_dwordx2 v[6:7], v[2:3], off offset:160
	global_load_dwordx4 v[2:5], v15, s[60:61] offset:352
	s_waitcnt vmcnt(0)
	v_pk_mul_f32 v[2:3], v[16:17], v[2:3]
	v_pk_mul_f32 v[16:17], v[30:31], v[0:1] op_sel_hi:[1,0]
	v_cvt_pk_bf16_f32 v2, v2, v3
	v_pk_mul_f32 v[4:5], v[16:17], v[4:5]
	v_pk_mul_f32 v[16:17], v[24:25], v[0:1] op_sel_hi:[1,0]
	v_cvt_pk_bf16_f32 v3, v4, v5
	global_store_dwordx2 v[6:7], v[2:3], off offset:176
	global_load_dwordx4 v[2:5], v15, s[60:61] offset:384
	s_waitcnt vmcnt(0)
	v_pk_mul_f32 v[2:3], v[16:17], v[2:3]
	v_pk_mul_f32 v[16:17], v[26:27], v[0:1] op_sel_hi:[1,0]
	v_cvt_pk_bf16_f32 v2, v2, v3
	v_pk_mul_f32 v[4:5], v[16:17], v[4:5]
	v_pk_mul_f32 v[16:17], v[20:21], v[0:1] op_sel_hi:[1,0]
	v_cvt_pk_bf16_f32 v3, v4, v5
	global_store_dwordx2 v[6:7], v[2:3], off offset:192
	global_load_dwordx4 v[2:5], v15, s[60:61] offset:416
	s_waitcnt vmcnt(0)
	v_pk_mul_f32 v[2:3], v[16:17], v[2:3]
	v_pk_mul_f32 v[16:17], v[22:23], v[0:1] op_sel_hi:[1,0]
	v_cvt_pk_bf16_f32 v2, v2, v3
	v_pk_mul_f32 v[4:5], v[16:17], v[4:5]
	v_pk_mul_f32 v[16:17], v[18:19], v[0:1] op_sel_hi:[1,0]
	v_cvt_pk_bf16_f32 v3, v4, v5
	global_store_dwordx2 v[6:7], v[2:3], off offset:208
	global_load_dwordx4 v[2:5], v15, s[60:61] offset:448
	s_waitcnt vmcnt(0)
	v_pk_mul_f32 v[2:3], v[16:17], v[2:3]
	v_pk_mul_f32 v[4:5], v[12:13], v[4:5]
	v_cvt_pk_bf16_f32 v2, v2, v3
	v_cvt_pk_bf16_f32 v3, v4, v5
	global_store_dwordx2 v[6:7], v[2:3], off offset:224
	global_load_dwordx4 v[2:5], v15, s[60:61] offset:480
	s_waitcnt vmcnt(0)
	v_pk_mul_f32 v[2:3], v[10:11], v[2:3]
	v_pk_mul_f32 v[4:5], v[8:9], v[4:5]
	v_cvt_pk_bf16_f32 v2, v2, v3
	v_cvt_pk_bf16_f32 v3, v4, v5
	global_store_dwordx2 v[6:7], v[2:3], off offset:240
	s_branch .LBB0_908
